# batched loads in serial round-trip loops: scan2 carry pass (8 loads per iteration), layer-0 norm gain/scale vectors (8 loads per row, counted waits), silu table fill (18 loads); plus earlier attention
# speedup vs baseline: 1.0193x; 1.0101x over previous
.LBB0_57:
	s_or_b64 exec, exec, s[4:5]
	s_movk_i32 s0, 0x2400
	v_cmp_gt_i32_e32 vcc, s0, v1
	s_waitcnt lgkmcnt(0)
	s_barrier
	s_and_saveexec_b64 s[0:1], vcc
	s_cbranch_execz .LBB0_64
	v_lshl_add_u32 v6, v1, 2, 0
	v_mov_b32_e32 v3, 0
	s_load_dwordx2 s[18:19], s[6:7], 0x28
	s_load_dwordx2 s[4:5], s[6:7], 0x30
	v_lshlrev_b32_e32 v4, 2, v1
	v_mov_b32_e32 v5, 0
	s_mov_b64 s[10:11], 0x1000
	s_waitcnt lgkmcnt(0)
	v_lshl_add_u64 v[8:9], s[4:5], 0, v[4:5]
	global_load_dword v226, v[8:9], off
	global_load_dword v227, v[8:9], off offset:2048
	v_lshl_add_u64 v[8:9], s[18:19], 0, v[4:5]
	global_load_dword v228, v[8:9], off
	global_load_dword v229, v[8:9], off offset:2048
	v_lshl_add_u64 v[8:9], v[8:9], 0, s[10:11]
	global_load_dword v230, v[8:9], off
	global_load_dword v231, v[8:9], off offset:2048
	v_lshl_add_u64 v[8:9], v[8:9], 0, s[10:11]
	global_load_dword v232, v[8:9], off
	global_load_dword v233, v[8:9], off offset:2048
	v_lshl_add_u64 v[8:9], v[8:9], 0, s[10:11]
	global_load_dword v234, v[8:9], off
	global_load_dword v235, v[8:9], off offset:2048
	v_lshl_add_u64 v[8:9], v[8:9], 0, s[10:11]
	global_load_dword v236, v[8:9], off
	global_load_dword v237, v[8:9], off offset:2048
	v_lshl_add_u64 v[8:9], v[8:9], 0, s[10:11]
	global_load_dword v238, v[8:9], off
	global_load_dword v239, v[8:9], off offset:2048
	v_lshl_add_u64 v[8:9], v[8:9], 0, s[10:11]
	global_load_dword v240, v[8:9], off
	global_load_dword v241, v[8:9], off offset:2048
	v_lshl_add_u64 v[8:9], v[8:9], 0, s[10:11]
	global_load_dword v242, v[8:9], off
	global_load_dword v243, v[8:9], off offset:2048
	s_waitcnt vmcnt(0)
	v_mov_b32_e32 v2, v226
	v_mul_f32_e32 v4, 0xbfb8aa3b, v2
	v_exp_f32_e32 v4, v4
	s_nop 0
	v_add_f32_e32 v4, 1.0, v4
	v_div_scale_f32 v7, s[8:9], v4, v4, v2
	v_rcp_f32_e32 v8, v7
	v_div_scale_f32 v9, vcc, v2, v4, v2
	v_fma_f32 v10, -v7, v8, 1.0
	v_fmac_f32_e32 v8, v10, v8
	v_mul_f32_e32 v10, v9, v8
	v_fma_f32 v11, -v7, v10, v9
	v_fmac_f32_e32 v10, v11, v8
	v_fma_f32 v7, -v7, v10, v9
	v_div_fmas_f32 v7, v7, v8, v10
	v_div_fixup_f32 v2, v7, v4, v2
	ds_write_b32 v6, v2
	v_mov_b32_e32 v2, v227
	v_mul_f32_e32 v4, 0xbfb8aa3b, v2
	v_exp_f32_e32 v4, v4
	s_nop 0
	v_add_f32_e32 v4, 1.0, v4
	v_div_scale_f32 v7, s[8:9], v4, v4, v2
	v_rcp_f32_e32 v8, v7
	v_div_scale_f32 v9, vcc, v2, v4, v2
	v_fma_f32 v10, -v7, v8, 1.0
	v_fmac_f32_e32 v8, v10, v8
	v_mul_f32_e32 v10, v9, v8
	v_fma_f32 v11, -v7, v10, v9
	v_fmac_f32_e32 v10, v11, v8
	v_fma_f32 v7, -v7, v10, v9
	v_div_fmas_f32 v7, v7, v8, v10
	v_div_fixup_f32 v2, v7, v4, v2
	ds_write_b32 v6, v2 offset:2048
	v_mov_b32_e32 v2, v228
	v_mul_f32_e32 v4, 0xbfb8aa3b, v2
	v_exp_f32_e32 v4, v4
	s_nop 0
	v_add_f32_e32 v4, 1.0, v4
	v_div_scale_f32 v7, s[8:9], v4, v4, v2
	v_rcp_f32_e32 v8, v7
	v_div_scale_f32 v9, vcc, v2, v4, v2
	v_fma_f32 v10, -v7, v8, 1.0
	v_fmac_f32_e32 v8, v10, v8
	v_mul_f32_e32 v10, v9, v8
	v_fma_f32 v11, -v7, v10, v9
	v_fmac_f32_e32 v10, v11, v8
	v_fma_f32 v7, -v7, v10, v9
	v_div_fmas_f32 v7, v7, v8, v10
	v_div_fixup_f32 v2, v7, v4, v2
	ds_write_b32 v6, v2 offset:4096
	v_mov_b32_e32 v2, v229
	v_mul_f32_e32 v4, 0xbfb8aa3b, v2
	v_exp_f32_e32 v4, v4
	s_nop 0
	v_add_f32_e32 v4, 1.0, v4
	v_div_scale_f32 v7, s[8:9], v4, v4, v2
	v_rcp_f32_e32 v8, v7
	v_div_scale_f32 v9, vcc, v2, v4, v2
	v_fma_f32 v10, -v7, v8, 1.0
	v_fmac_f32_e32 v8, v10, v8
	v_mul_f32_e32 v10, v9, v8
	v_fma_f32 v11, -v7, v10, v9
	v_fmac_f32_e32 v10, v11, v8
	v_fma_f32 v7, -v7, v10, v9
	v_div_fmas_f32 v7, v7, v8, v10
	v_div_fixup_f32 v2, v7, v4, v2
	ds_write_b32 v6, v2 offset:6144
	v_mov_b32_e32 v2, v230
	v_mul_f32_e32 v4, 0xbfb8aa3b, v2
	v_exp_f32_e32 v4, v4
	s_nop 0
	v_add_f32_e32 v4, 1.0, v4
	v_div_scale_f32 v7, s[8:9], v4, v4, v2
	v_rcp_f32_e32 v8, v7
	v_div_scale_f32 v9, vcc, v2, v4, v2
	v_fma_f32 v10, -v7, v8, 1.0
	v_fmac_f32_e32 v8, v10, v8
	v_mul_f32_e32 v10, v9, v8
	v_fma_f32 v11, -v7, v10, v9
	v_fmac_f32_e32 v10, v11, v8
	v_fma_f32 v7, -v7, v10, v9
	v_div_fmas_f32 v7, v7, v8, v10
	v_div_fixup_f32 v2, v7, v4, v2
	ds_write_b32 v6, v2 offset:8192
	v_mov_b32_e32 v2, v231
	v_mul_f32_e32 v4, 0xbfb8aa3b, v2
	v_exp_f32_e32 v4, v4
	s_nop 0
	v_add_f32_e32 v4, 1.0, v4
	v_div_scale_f32 v7, s[8:9], v4, v4, v2
	v_rcp_f32_e32 v8, v7
	v_div_scale_f32 v9, vcc, v2, v4, v2
	v_fma_f32 v10, -v7, v8, 1.0
	v_fmac_f32_e32 v8, v10, v8
	v_mul_f32_e32 v10, v9, v8
	v_fma_f32 v11, -v7, v10, v9
	v_fmac_f32_e32 v10, v11, v8
	v_fma_f32 v7, -v7, v10, v9
	v_div_fmas_f32 v7, v7, v8, v10
	v_div_fixup_f32 v2, v7, v4, v2
	ds_write_b32 v6, v2 offset:10240
	v_mov_b32_e32 v2, v232
	v_mul_f32_e32 v4, 0xbfb8aa3b, v2
	v_exp_f32_e32 v4, v4
	s_nop 0
	v_add_f32_e32 v4, 1.0, v4
	v_div_scale_f32 v7, s[8:9], v4, v4, v2
	v_rcp_f32_e32 v8, v7
	v_div_scale_f32 v9, vcc, v2, v4, v2
	v_fma_f32 v10, -v7, v8, 1.0
	v_fmac_f32_e32 v8, v10, v8
	v_mul_f32_e32 v10, v9, v8
	v_fma_f32 v11, -v7, v10, v9
	v_fmac_f32_e32 v10, v11, v8
	v_fma_f32 v7, -v7, v10, v9
	v_div_fmas_f32 v7, v7, v8, v10
	v_div_fixup_f32 v2, v7, v4, v2
	ds_write_b32 v6, v2 offset:12288
	v_mov_b32_e32 v2, v233
	v_mul_f32_e32 v4, 0xbfb8aa3b, v2
	v_exp_f32_e32 v4, v4
	s_nop 0
	v_add_f32_e32 v4, 1.0, v4
	v_div_scale_f32 v7, s[8:9], v4, v4, v2
	v_rcp_f32_e32 v8, v7
	v_div_scale_f32 v9, vcc, v2, v4, v2
	v_fma_f32 v10, -v7, v8, 1.0
	v_fmac_f32_e32 v8, v10, v8
	v_mul_f32_e32 v10, v9, v8
	v_fma_f32 v11, -v7, v10, v9
	v_fmac_f32_e32 v10, v11, v8
	v_fma_f32 v7, -v7, v10, v9
	v_div_fmas_f32 v7, v7, v8, v10
	v_div_fixup_f32 v2, v7, v4, v2
	ds_write_b32 v6, v2 offset:14336
	v_mov_b32_e32 v2, v234
	v_mul_f32_e32 v4, 0xbfb8aa3b, v2
	v_exp_f32_e32 v4, v4
	s_nop 0
	v_add_f32_e32 v4, 1.0, v4
	v_div_scale_f32 v7, s[8:9], v4, v4, v2
	v_rcp_f32_e32 v8, v7
	v_div_scale_f32 v9, vcc, v2, v4, v2
	v_fma_f32 v10, -v7, v8, 1.0
	v_fmac_f32_e32 v8, v10, v8
	v_mul_f32_e32 v10, v9, v8
	v_fma_f32 v11, -v7, v10, v9
	v_fmac_f32_e32 v10, v11, v8
	v_fma_f32 v7, -v7, v10, v9
	v_div_fmas_f32 v7, v7, v8, v10
	v_div_fixup_f32 v2, v7, v4, v2
	ds_write_b32 v6, v2 offset:16384
	v_mov_b32_e32 v2, v235
	v_mul_f32_e32 v4, 0xbfb8aa3b, v2
	v_exp_f32_e32 v4, v4
	s_nop 0
	v_add_f32_e32 v4, 1.0, v4
	v_div_scale_f32 v7, s[8:9], v4, v4, v2
	v_rcp_f32_e32 v8, v7
	v_div_scale_f32 v9, vcc, v2, v4, v2
	v_fma_f32 v10, -v7, v8, 1.0
	v_fmac_f32_e32 v8, v10, v8
	v_mul_f32_e32 v10, v9, v8
	v_fma_f32 v11, -v7, v10, v9
	v_fmac_f32_e32 v10, v11, v8
	v_fma_f32 v7, -v7, v10, v9
	v_div_fmas_f32 v7, v7, v8, v10
	v_div_fixup_f32 v2, v7, v4, v2
	ds_write_b32 v6, v2 offset:18432
	v_mov_b32_e32 v2, v236
	v_mul_f32_e32 v4, 0xbfb8aa3b, v2
	v_exp_f32_e32 v4, v4
	s_nop 0
	v_add_f32_e32 v4, 1.0, v4
	v_div_scale_f32 v7, s[8:9], v4, v4, v2
	v_rcp_f32_e32 v8, v7
	v_div_scale_f32 v9, vcc, v2, v4, v2
	v_fma_f32 v10, -v7, v8, 1.0
	v_fmac_f32_e32 v8, v10, v8
	v_mul_f32_e32 v10, v9, v8
	v_fma_f32 v11, -v7, v10, v9
	v_fmac_f32_e32 v10, v11, v8
	v_fma_f32 v7, -v7, v10, v9
	v_div_fmas_f32 v7, v7, v8, v10
	v_div_fixup_f32 v2, v7, v4, v2
	ds_write_b32 v6, v2 offset:20480
	v_mov_b32_e32 v2, v237
	v_mul_f32_e32 v4, 0xbfb8aa3b, v2
	v_exp_f32_e32 v4, v4
	s_nop 0
	v_add_f32_e32 v4, 1.0, v4
	v_div_scale_f32 v7, s[8:9], v4, v4, v2
	v_rcp_f32_e32 v8, v7
	v_div_scale_f32 v9, vcc, v2, v4, v2
	v_fma_f32 v10, -v7, v8, 1.0
	v_fmac_f32_e32 v8, v10, v8
	v_mul_f32_e32 v10, v9, v8
	v_fma_f32 v11, -v7, v10, v9
	v_fmac_f32_e32 v10, v11, v8
	v_fma_f32 v7, -v7, v10, v9
	v_div_fmas_f32 v7, v7, v8, v10
	v_div_fixup_f32 v2, v7, v4, v2
	ds_write_b32 v6, v2 offset:22528
	v_mov_b32_e32 v2, v238
	v_mul_f32_e32 v4, 0xbfb8aa3b, v2
	v_exp_f32_e32 v4, v4
	s_nop 0
	v_add_f32_e32 v4, 1.0, v4
	v_div_scale_f32 v7, s[8:9], v4, v4, v2
	v_rcp_f32_e32 v8, v7
	v_div_scale_f32 v9, vcc, v2, v4, v2
	v_fma_f32 v10, -v7, v8, 1.0
	v_fmac_f32_e32 v8, v10, v8
	v_mul_f32_e32 v10, v9, v8
	v_fma_f32 v11, -v7, v10, v9
	v_fmac_f32_e32 v10, v11, v8
	v_fma_f32 v7, -v7, v10, v9
	v_div_fmas_f32 v7, v7, v8, v10
	v_div_fixup_f32 v2, v7, v4, v2
	ds_write_b32 v6, v2 offset:24576
	v_mov_b32_e32 v2, v239
	v_mul_f32_e32 v4, 0xbfb8aa3b, v2
	v_exp_f32_e32 v4, v4
	s_nop 0
	v_add_f32_e32 v4, 1.0, v4
	v_div_scale_f32 v7, s[8:9], v4, v4, v2
	v_rcp_f32_e32 v8, v7
	v_div_scale_f32 v9, vcc, v2, v4, v2
	v_fma_f32 v10, -v7, v8, 1.0
	v_fmac_f32_e32 v8, v10, v8
	v_mul_f32_e32 v10, v9, v8
	v_fma_f32 v11, -v7, v10, v9
	v_fmac_f32_e32 v10, v11, v8
	v_fma_f32 v7, -v7, v10, v9
	v_div_fmas_f32 v7, v7, v8, v10
	v_div_fixup_f32 v2, v7, v4, v2
	ds_write_b32 v6, v2 offset:26624
	v_mov_b32_e32 v2, v240
	v_mul_f32_e32 v4, 0xbfb8aa3b, v2
	v_exp_f32_e32 v4, v4
	s_nop 0
	v_add_f32_e32 v4, 1.0, v4
	v_div_scale_f32 v7, s[8:9], v4, v4, v2
	v_rcp_f32_e32 v8, v7
	v_div_scale_f32 v9, vcc, v2, v4, v2
	v_fma_f32 v10, -v7, v8, 1.0
	v_fmac_f32_e32 v8, v10, v8
	v_mul_f32_e32 v10, v9, v8
	v_fma_f32 v11, -v7, v10, v9
	v_fmac_f32_e32 v10, v11, v8
	v_fma_f32 v7, -v7, v10, v9
	v_div_fmas_f32 v7, v7, v8, v10
	v_div_fixup_f32 v2, v7, v4, v2
	ds_write_b32 v6, v2 offset:28672
	v_mov_b32_e32 v2, v241
	v_mul_f32_e32 v4, 0xbfb8aa3b, v2
	v_exp_f32_e32 v4, v4
	s_nop 0
	v_add_f32_e32 v4, 1.0, v4
	v_div_scale_f32 v7, s[8:9], v4, v4, v2
	v_rcp_f32_e32 v8, v7
	v_div_scale_f32 v9, vcc, v2, v4, v2
	v_fma_f32 v10, -v7, v8, 1.0
	v_fmac_f32_e32 v8, v10, v8
	v_mul_f32_e32 v10, v9, v8
	v_fma_f32 v11, -v7, v10, v9
	v_fmac_f32_e32 v10, v11, v8
	v_fma_f32 v7, -v7, v10, v9
	v_div_fmas_f32 v7, v7, v8, v10
	v_div_fixup_f32 v2, v7, v4, v2
	ds_write_b32 v6, v2 offset:30720
	v_mov_b32_e32 v2, v242
	v_mul_f32_e32 v4, 0xbfb8aa3b, v2
	v_exp_f32_e32 v4, v4
	s_nop 0
	v_add_f32_e32 v4, 1.0, v4
	v_div_scale_f32 v7, s[8:9], v4, v4, v2
	v_rcp_f32_e32 v8, v7
	v_div_scale_f32 v9, vcc, v2, v4, v2
	v_fma_f32 v10, -v7, v8, 1.0
	v_fmac_f32_e32 v8, v10, v8
	v_mul_f32_e32 v10, v9, v8
	v_fma_f32 v11, -v7, v10, v9
	v_fmac_f32_e32 v10, v11, v8
	v_fma_f32 v7, -v7, v10, v9
	v_div_fmas_f32 v7, v7, v8, v10
	v_div_fixup_f32 v2, v7, v4, v2
	ds_write_b32 v6, v2 offset:32768
	v_mov_b32_e32 v2, v243
	v_mul_f32_e32 v4, 0xbfb8aa3b, v2
	v_exp_f32_e32 v4, v4
	s_nop 0
	v_add_f32_e32 v4, 1.0, v4
	v_div_scale_f32 v7, s[8:9], v4, v4, v2
	v_rcp_f32_e32 v8, v7
	v_div_scale_f32 v9, vcc, v2, v4, v2
	v_fma_f32 v10, -v7, v8, 1.0
	v_fmac_f32_e32 v8, v10, v8
	v_mul_f32_e32 v10, v9, v8
	v_fma_f32 v11, -v7, v10, v9
	v_fmac_f32_e32 v10, v11, v8
	v_fma_f32 v7, -v7, v10, v9
	v_div_fmas_f32 v7, v7, v8, v10
	v_div_fixup_f32 v2, v7, v4, v2
	ds_write_b32 v6, v2 offset:34816

.LBB0_133:
	s_andn2_b64 vcc, exec, s[0:1]
	s_cbranch_vccnz .LBB0_238
	v_readlane_b32 s26, v254, 0
	v_readlane_b32 s27, v254, 1
	s_load_dwordx2 s[0:1], s[26:27], 0xf0
	v_mov_b32_e32 v0, v179
	s_mov_b32 s2, s39
	s_lshl_b32 s18, s2, 3
	v_ashrrev_i32_e32 v18, 6, v0
	v_add_u32_e32 v43, s18, v18
	v_cmp_gt_i32_e32 vcc, s9, v43
	s_and_saveexec_b64 s[2:3], vcc
	s_cbranch_execz .LBB0_141
	s_waitcnt lgkmcnt(0)
	s_load_dwordx4 s[48:51], s[26:27], 0x0
	s_load_dwordx2 s[16:17], s[26:27], 0x48
	v_and_b32_e32 v21, 63, v0
	v_add_u32_e32 v0, 0xfffff000, v43
	v_ashrrev_i32_e32 v2, 31, v43
	v_cmp_gt_i32_e32 vcc, s24, v43
	s_waitcnt lgkmcnt(0)
	v_mov_b32_e32 v4, s49
	v_ashrrev_i32_e32 v19, 31, v18
	v_cndmask_b32_e32 v3, 0, v2, vcc
	v_cndmask_b32_e32 v2, v0, v43, vcc
	v_mov_b32_e32 v0, s51
	v_cndmask_b32_e32 v5, v0, v4, vcc
	v_mov_b32_e32 v0, s50
	v_mov_b32_e32 v4, s48
	v_cndmask_b32_e32 v4, v0, v4, vcc
	v_lshlrev_b64 v[2:3], 12, v[2:3]
	v_lshl_add_u64 v[2:3], v[4:5], 0, v[2:3]
	v_lshlrev_b32_e32 v0, 4, v21
	v_lshl_add_u64 v[2:3], v[2:3], 0, v[0:1]
	global_load_dwordx4 v[14:17], v[2:3], off
	global_load_dwordx4 v[10:13], v[2:3], off offset:1024
	global_load_dwordx4 v[6:9], v[2:3], off offset:2048
	s_nop 0
	global_load_dwordx4 v[2:5], v[2:3], off offset:3072
	s_ashr_i32 s19, s18, 31
	v_lshl_add_u64 v[18:19], v[18:19], 0, s[18:19]
	v_lshlrev_b32_e32 v34, 2, v21
	v_mov_b32_e32 v35, v1
	v_lshlrev_b64 v[24:25], 6, v[18:19]
	v_lshl_add_u64 v[24:25], v[24:25], 0, v[34:35]
	v_lshlrev_b64 v[18:19], 11, v[18:19]
	v_lshl_add_u64 v[36:37], s[16:17], 0, v[0:1]
	v_lshl_add_u64 v[24:25], s[0:1], 0, v[24:25]
	s_mov_b64 s[16:17], 0x5e00000
	v_lshl_or_b32 v18, v21, 3, v18
	v_or_b32_e32 v0, 0x100, v34
	v_or_b32_e32 v20, 0x200, v34
	v_or_b32_e32 v22, 0x300, v34
	v_lshl_add_u64 v[38:39], v[24:25], 0, s[16:17]
	v_lshl_add_u64 v[18:19], s[0:1], 0, v[18:19]
	s_mov_b64 s[16:17], 0x6000400
	v_xor_b32_e32 v48, 4, v34
	v_xor_b32_e32 v49, 8, v34
	v_xor_b32_e32 v50, 16, v34
	v_xor_b32_e32 v51, 32, v34
	v_xor_b32_e32 v52, 64, v34
	v_xor_b32_e32 v53, 0x80, v34
	v_cmp_gt_u32_e32 vcc, 16, v21
	v_cmp_eq_u32_e64 s[40:41], 0, v21
	v_lshl_add_u64 v[40:41], v[18:19], 0, s[16:17]
	s_mov_b64 s[26:27], 0
	v_lshlrev_b32_e32 v42, 2, v0
	v_lshlrev_b32_e32 v44, 2, v20
	v_lshlrev_b32_e32 v46, 2, v22
	s_waitcnt vmcnt(0)
	s_branch .LBB0_137
.LBB0_136:
	s_or_b64 exec, exec, s[18:19]
	v_add_u32_e32 v43, 0xfffff000, v43
	v_ashrrev_i32_e32 v43, 11, v43
	v_add_u32_e32 v43, 1, v43
	v_cndmask_b32_e64 v43, 0, v43, s[44:45]
	v_mul_hi_i32_i24_e32 v55, 0x6000, v43
	v_mul_i32_i24_e32 v54, 0x6000, v43
	v_lshl_add_u64 v[54:55], s[0:1], 0, v[54:55]
	s_mov_b64 s[16:17], 0x1000
	v_lshl_add_u64 v[62:63], v[54:55], 0, s[16:17]
	v_lshl_add_u64 v[58:59], v[62:63], 0, v[0:1]
	v_mov_b32_e32 v43, v1
	v_mov_b32_e32 v45, v1
	v_mov_b32_e32 v47, v1
	global_load_dwordx4 v[64:67], v[36:37], off
	global_load_dwordx4 v[68:71], v[58:59], off
	v_lshl_add_u64 v[54:55], v[62:63], 0, v[42:43]
	global_load_dwordx4 v[72:75], v[36:37], off offset:1024
	global_load_dwordx4 v[76:79], v[54:55], off
	v_lshl_add_u64 v[54:55], v[62:63], 0, v[44:45]
	global_load_dwordx4 v[80:83], v[36:37], off offset:2048
	global_load_dwordx4 v[84:87], v[54:55], off
	v_lshl_add_u64 v[54:55], v[62:63], 0, v[46:47]
	global_load_dwordx4 v[88:91], v[36:37], off offset:3072
	global_load_dwordx4 v[92:95], v[54:55], off
	s_waitcnt lgkmcnt(0)
	s_and_b64 s[16:17], exec, s[42:43]
	v_readlane_b32 s18, v255, 23
	s_or_b64 s[26:27], s[16:17], s[26:27]
	v_readlane_b32 s16, v255, 25
	v_readlane_b32 s19, v255, 24
	v_readlane_b32 s17, v255, 26
	v_lshl_add_u64 v[38:39], v[38:39], 0, s[18:19]
	v_mov_b32_e32 v43, v35
	s_waitcnt vmcnt(6)
	v_pk_mul_f32 v[16:17], v[16:17], v[66:67]
	v_pk_mul_f32 v[14:15], v[14:15], v[64:65]
	v_pk_add_f32 v[56:57], v[68:69], 1.0 op_sel_hi:[1,0]
	v_pk_add_f32 v[54:55], v[70:71], 1.0 op_sel_hi:[1,0]
	v_pk_mul_f32 v[14:15], v[14:15], v[56:57]
	v_pk_mul_f32 v[16:17], v[16:17], v[54:55]
	v_cvt_pk_bf16_f32 v14, v14, v15
	v_cvt_pk_bf16_f32 v15, v16, v17
	global_store_dwordx2 v[40:41], v[14:15], off offset:-1024
	s_waitcnt vmcnt(5)
	v_pk_mul_f32 v[12:13], v[12:13], v[74:75]
	v_pk_mul_f32 v[10:11], v[10:11], v[72:73]
	v_pk_add_f32 v[56:57], v[76:77], 1.0 op_sel_hi:[1,0]
	v_pk_add_f32 v[54:55], v[78:79], 1.0 op_sel_hi:[1,0]
	v_pk_mul_f32 v[10:11], v[10:11], v[56:57]
	v_pk_mul_f32 v[12:13], v[12:13], v[54:55]
	v_cvt_pk_bf16_f32 v10, v10, v11
	v_cvt_pk_bf16_f32 v11, v12, v13
	global_store_dwordx2 v[40:41], v[10:11], off offset:-512
	s_waitcnt vmcnt(4)
	v_pk_mul_f32 v[8:9], v[8:9], v[82:83]
	v_pk_mul_f32 v[6:7], v[6:7], v[80:81]
	v_pk_add_f32 v[56:57], v[84:85], 1.0 op_sel_hi:[1,0]
	v_pk_add_f32 v[54:55], v[86:87], 1.0 op_sel_hi:[1,0]
	v_pk_mul_f32 v[6:7], v[6:7], v[56:57]
	v_pk_mul_f32 v[8:9], v[8:9], v[54:55]
	v_cvt_pk_bf16_f32 v6, v6, v7
	v_cvt_pk_bf16_f32 v7, v8, v9
	global_store_dwordx2 v[40:41], v[6:7], off
	s_waitcnt vmcnt(3)
	v_pk_mul_f32 v[4:5], v[4:5], v[90:91]
	v_pk_mul_f32 v[2:3], v[2:3], v[88:89]
	v_pk_add_f32 v[56:57], v[92:93], 1.0 op_sel_hi:[1,0]
	v_pk_add_f32 v[54:55], v[94:95], 1.0 op_sel_hi:[1,0]
	v_pk_mul_f32 v[2:3], v[2:3], v[56:57]
	v_pk_mul_f32 v[4:5], v[4:5], v[54:55]
	v_cvt_pk_bf16_f32 v2, v2, v3
	v_cvt_pk_bf16_f32 v3, v4, v5
	global_store_dwordx2 v[40:41], v[2:3], off offset:512
	v_mov_b32_e32 v14, v22
	v_mov_b32_e32 v15, v23
	v_mov_b32_e32 v16, v24
	v_mov_b32_e32 v17, v25
	v_mov_b32_e32 v10, v26
	v_mov_b32_e32 v11, v27
	v_mov_b32_e32 v12, v28
	v_mov_b32_e32 v13, v29
	v_mov_b32_e32 v6, v30
	v_mov_b32_e32 v7, v31
	v_mov_b32_e32 v8, v32
	v_mov_b32_e32 v9, v33
	v_mov_b32_e32 v2, v18
	v_mov_b32_e32 v3, v19
	v_mov_b32_e32 v4, v20
	v_mov_b32_e32 v5, v21
	v_lshl_add_u64 v[40:41], v[40:41], 0, s[16:17]
	s_andn2_b64 exec, exec, s[26:27]
	s_cbranch_execz .LBB0_141
.LBB0_137:
	s_movk_i32 s16, 0xfff
	v_cmp_lt_i32_e64 s[44:45], s16, v43
	v_readlane_b32 s16, v255, 15
	v_lshlrev_b32_e32 v0, 2, v34
	s_waitcnt vmcnt(4)
	v_mov_b32_e32 v22, v14
	v_add_u32_e32 v35, s16, v43
	s_movk_i32 s16, 0x4fff
	v_cmp_gt_i32_e64 s[46:47], s9, v35
	v_cmp_lt_i32_e64 s[42:43], s16, v35
	v_mov_b32_e32 v23, v15
	v_mov_b32_e32 v24, v16
	v_mov_b32_e32 v25, v17
	s_waitcnt vmcnt(4)
	v_mov_b32_e32 v26, v10
	v_mov_b32_e32 v27, v11
	v_mov_b32_e32 v28, v12
	v_mov_b32_e32 v29, v13
	s_waitcnt vmcnt(4)
	v_mov_b32_e32 v30, v6
	v_mov_b32_e32 v31, v7
	v_mov_b32_e32 v32, v8
	v_mov_b32_e32 v33, v9
	s_waitcnt vmcnt(4)
	v_mov_b32_e32 v18, v2
	v_mov_b32_e32 v19, v3
	v_mov_b32_e32 v20, v4
	v_mov_b32_e32 v21, v5
	v_readlane_b32 s17, v255, 16
	s_and_saveexec_b64 s[18:19], s[46:47]
	s_cbranch_execz .LBB0_139
	v_add_u32_e32 v18, 0xfffff000, v35
	v_ashrrev_i32_e32 v19, 31, v35
	v_cmp_gt_i32_e64 s[46:47], s24, v35
	v_mov_b32_e32 v20, s51
	v_mov_b32_e32 v21, s49
	v_cndmask_b32_e64 v19, 0, v19, s[46:47]
	v_cndmask_b32_e64 v18, v18, v35, s[46:47]
	v_cndmask_b32_e64 v21, v20, v21, s[46:47]
	v_mov_b32_e32 v20, s50
	v_mov_b32_e32 v22, s48
	v_cndmask_b32_e64 v20, v20, v22, s[46:47]
	v_lshlrev_b64 v[18:19], 12, v[18:19]
	v_lshl_add_u64 v[18:19], v[20:21], 0, v[18:19]
	v_lshl_add_u64 v[18:19], v[18:19], 0, v[0:1]
	global_load_dwordx4 v[22:25], v[18:19], off
	global_load_dwordx4 v[26:29], v[18:19], off offset:1024
	global_load_dwordx4 v[30:33], v[18:19], off offset:2048
	s_nop 0
	global_load_dwordx4 v[18:21], v[18:19], off offset:3072

.LBB0_1155:
	v_mov_b32_e32 v10, s16
	s_not_b32 s17, s16
	v_add_u32_e32 v12, s17, v5
	v_cndmask_b32_e64 v12, v12, v10, s[40:41]
	v_ashrrev_i32_e32 v13, 31, v12
	v_lshlrev_b64 v[12:13], 13, v[12:13]
	v_lshl_add_u64 v[16:17], v[8:9], 0, v[12:13]
	global_load_dwordx2 v[32:33], v[16:17], off
	s_add_i32 s17, s16, 1
	v_mov_b32_e32 v10, s17
	s_not_b32 s17, s17
	v_add_u32_e32 v12, s17, v5
	v_cndmask_b32_e64 v12, v12, v10, s[40:41]
	v_ashrrev_i32_e32 v13, 31, v12
	v_lshlrev_b64 v[12:13], 13, v[12:13]
	v_lshl_add_u64 v[18:19], v[8:9], 0, v[12:13]
	global_load_dwordx2 v[34:35], v[18:19], off
	s_add_i32 s17, s16, 2
	v_mov_b32_e32 v10, s17
	s_not_b32 s17, s17
	v_add_u32_e32 v12, s17, v5
	v_cndmask_b32_e64 v12, v12, v10, s[40:41]
	v_ashrrev_i32_e32 v13, 31, v12
	v_lshlrev_b64 v[12:13], 13, v[12:13]
	v_lshl_add_u64 v[20:21], v[8:9], 0, v[12:13]
	global_load_dwordx2 v[36:37], v[20:21], off
	s_add_i32 s17, s16, 3
	v_mov_b32_e32 v10, s17
	s_not_b32 s17, s17
	v_add_u32_e32 v12, s17, v5
	v_cndmask_b32_e64 v12, v12, v10, s[40:41]
	v_ashrrev_i32_e32 v13, 31, v12
	v_lshlrev_b64 v[12:13], 13, v[12:13]
	v_lshl_add_u64 v[22:23], v[8:9], 0, v[12:13]
	global_load_dwordx2 v[38:39], v[22:23], off
	s_add_i32 s17, s16, 4
	v_mov_b32_e32 v10, s17
	s_not_b32 s17, s17
	v_add_u32_e32 v12, s17, v5
	v_cndmask_b32_e64 v12, v12, v10, s[40:41]
	v_ashrrev_i32_e32 v13, 31, v12
	v_lshlrev_b64 v[12:13], 13, v[12:13]
	v_lshl_add_u64 v[24:25], v[8:9], 0, v[12:13]
	global_load_dwordx2 v[40:41], v[24:25], off
	s_add_i32 s17, s16, 5
	v_mov_b32_e32 v10, s17
	s_not_b32 s17, s17
	v_add_u32_e32 v12, s17, v5
	v_cndmask_b32_e64 v12, v12, v10, s[40:41]
	v_ashrrev_i32_e32 v13, 31, v12
	v_lshlrev_b64 v[12:13], 13, v[12:13]
	v_lshl_add_u64 v[26:27], v[8:9], 0, v[12:13]
	global_load_dwordx2 v[42:43], v[26:27], off
	s_add_i32 s17, s16, 6
	v_mov_b32_e32 v10, s17
	s_not_b32 s17, s17
	v_add_u32_e32 v12, s17, v5
	v_cndmask_b32_e64 v12, v12, v10, s[40:41]
	v_ashrrev_i32_e32 v13, 31, v12
	v_lshlrev_b64 v[12:13], 13, v[12:13]
	v_lshl_add_u64 v[28:29], v[8:9], 0, v[12:13]
	global_load_dwordx2 v[44:45], v[28:29], off
	s_add_i32 s17, s16, 7
	v_mov_b32_e32 v10, s17
	s_not_b32 s17, s17
	v_add_u32_e32 v12, s17, v5
	v_cndmask_b32_e64 v12, v12, v10, s[40:41]
	v_ashrrev_i32_e32 v13, 31, v12
	v_lshlrev_b64 v[12:13], 13, v[12:13]
	v_lshl_add_u64 v[30:31], v[8:9], 0, v[12:13]
	global_load_dwordx2 v[46:47], v[30:31], off
	s_add_i32 s16, s16, 8
	v_cmp_eq_u32_e64 s[42:43], s16, v5
	s_or_b64 s[36:37], s[42:43], s[36:37]
	s_waitcnt vmcnt(7)
	global_store_dword v[16:17], v11, off offset:4
	v_mul_f32_e32 v10, 0x3fb8aa3b, v32
	v_exp_f32_e32 v10, v10
	s_nop 0
	v_fmac_f32_e32 v33, v11, v10
	v_mov_b32_e32 v11, v33
	s_waitcnt vmcnt(7)
	global_store_dword v[18:19], v11, off offset:4
	v_mul_f32_e32 v10, 0x3fb8aa3b, v34
	v_exp_f32_e32 v10, v10
	s_nop 0
	v_fmac_f32_e32 v35, v11, v10
	v_mov_b32_e32 v11, v35
	s_waitcnt vmcnt(7)
	global_store_dword v[20:21], v11, off offset:4
	v_mul_f32_e32 v10, 0x3fb8aa3b, v36
	v_exp_f32_e32 v10, v10
	s_nop 0
	v_fmac_f32_e32 v37, v11, v10
	v_mov_b32_e32 v11, v37
	s_waitcnt vmcnt(7)
	global_store_dword v[22:23], v11, off offset:4
	v_mul_f32_e32 v10, 0x3fb8aa3b, v38
	v_exp_f32_e32 v10, v10
	s_nop 0
	v_fmac_f32_e32 v39, v11, v10
	v_mov_b32_e32 v11, v39
	s_waitcnt vmcnt(7)
	global_store_dword v[24:25], v11, off offset:4
	v_mul_f32_e32 v10, 0x3fb8aa3b, v40
	v_exp_f32_e32 v10, v10
	s_nop 0
	v_fmac_f32_e32 v41, v11, v10
	v_mov_b32_e32 v11, v41
	s_waitcnt vmcnt(7)
	global_store_dword v[26:27], v11, off offset:4
	v_mul_f32_e32 v10, 0x3fb8aa3b, v42
	v_exp_f32_e32 v10, v10
	s_nop 0
	v_fmac_f32_e32 v43, v11, v10
	v_mov_b32_e32 v11, v43
	s_waitcnt vmcnt(7)
	global_store_dword v[28:29], v11, off offset:4
	v_mul_f32_e32 v10, 0x3fb8aa3b, v44
	v_exp_f32_e32 v10, v10
	s_nop 0
	v_fmac_f32_e32 v45, v11, v10
	v_mov_b32_e32 v11, v45
	s_waitcnt vmcnt(7)
	global_store_dword v[30:31], v11, off offset:4
	v_mul_f32_e32 v10, 0x3fb8aa3b, v46
	v_exp_f32_e32 v10, v10
	s_nop 0
	v_fmac_f32_e32 v47, v11, v10
	v_mov_b32_e32 v11, v47
	s_andn2_b64 exec, exec, s[36:37]
	s_cbranch_execnz .LBB0_1155
	s_or_b64 exec, exec, s[36:37]
	s_and_saveexec_b64 s[18:19], vcc
	s_cbranch_execz .LBB0_1149
	v_ashrrev_i32_e32 v5, 31, v4
	v_lshlrev_b64 v[4:5], 14, v[4:5]
	v_lshl_add_u64 v[4:5], s[30:31], 0, v[4:5]
	v_lshlrev_b64 v[6:7], 12, v[6:7]
	v_lshl_add_u64 v[4:5], v[4:5], 0, v[6:7]
	v_lshlrev_b32_e32 v0, 2, v2
	v_lshl_add_u64 v[4:5], v[4:5], 0, v[0:1]
	global_store_dword v[4:5], v11, off
	s_branch .LBB0_1149
